# fused S1 epilogue with in-LDS chunk-carry scan; removed SBUF round trip, one grid barrier and s2 phase per layer
# speedup vs baseline: 1.0266x; 1.0266x over previous
;     __device__ __forceinline__ void operator()(const AccT& acc, const Unit& u, int wr, int wc, int fr, int fq) const {
;     ...
;                 const int row = u.pm * 256 + ai * 128 + wr * 64 + m * 16 + fr;
;                 float* rp = SBUF + ((size_t)u.g * RG + row) * 256 + u.pn * 256 + wc * 32 + 8 * fq;
; #pragma unroll
;                 for (int bj = 0; bj < 2; ++bj) { *(f32x4*)(rp + bj * 128) = acc[ai][bj][m][0]; *(f32x4*)(rp + bj * 128 + 4) = acc[ai][bj][m][1]; }
; __device__ __forceinline__ void s2_phase(const float* SBUF, bf16_t* ACOMB, const float* lamT, int bx, int tid) {
;     if (bx >= 128) return;
;     const int idx = bx * 512 + tid, p = idx & 63, d = (idx >> 6) & 1, b = (idx >> 7) & 7, g = idx >> 10;
;     const float lr = lamT[((size_t)(g * 2 + d) * 64 + p) * 2], li = lamT[((size_t)(g * 2 + d) * 64 + p) * 2 + 1];
;     const float* sp = SBUF + ((size_t)g * RG + b * 64) * 256 + d * 128 + p;
;     bf16_t* xp = ACOMB + ((size_t)g * RG + b * 64) * KA + 512 + d * 128 + p;
;     float xr = 0.f, xi = 0.f;
;     for (int blk = 0; blk < 2; ++blk) {
;         float sr[32], si[32];
; #pragma unroll
;         for (int k = 0; k < 32; ++k) { const int c = (d == 0) ? (blk * 32 + k) : (63 - (blk * 32 + k)); sr[k] = sp[(size_t)c * 256]; si[k] = sp[(size_t)c * 256 + 64]; }
.LBB0_394:
	s_waitcnt vmcnt(0)
	s_barrier
	s_load_dwordx2 s[4:5], s[0:1], 0xc8
	v_and_b32_e32 v138, 63, v234
	v_lshrrev_b32_e32 v139, 6, v234
	v_and_b32_e32 v128, 15, v138
	v_lshrrev_b32_e32 v129, 4, v138
	v_lshrrev_b32_e32 v130, 2, v139
	v_and_b32_e32 v131, 3, v139
	v_lshl_add_u32 v130, v130, 6, v128
	v_mul_u32_u24_e32 v130, 0x210, v130
	v_lshlrev_b32_e32 v131, 7, v131
	v_lshl_add_u32 v131, v129, 5, v131
	v_add_u32_e32 v128, v130, v131
	v_add_u32_e32 v129, 0x10800, v128
	v_lshrrev_b32_e32 v130, 6, v234
	v_mul_u32_u24_e32 v130, 0x8400, v130
	v_lshl_add_u32 v130, v138, 2, v130
	v_lshrrev_b32_e32 v131, 4, v234
	v_and_b32_e32 v132, 15, v234
	v_mul_u32_u24_e32 v133, 0x600, v131
	v_lshl_add_u32 v133, v132, 4, v133
	v_mul_u32_u24_e32 v131, 0x210, v131
	v_lshl_add_u32 v131, v132, 5, v131
	v_add_u32_e32 v132, 0x10800, v131
	v_lshlrev_b32_e32 v136, 3, v138
	s_mul_i32 s8, s22, 0xc0000
	s_mul_i32 s9, s23, 0x60000
	s_add_i32 s8, s8, s9
	s_add_i32 s8, s8, 0x1aa00400
	s_lshl_b32 s9, s80, 16
	s_lshl_b32 s16, s22, 10
	s_add_i32 s9, s9, s16
	s_add_i32 s9, s9, 0x80000
	s_waitcnt lgkmcnt(0)
	s_add_u32 s6, s4, s8
	s_addc_u32 s7, s5, 0
	s_add_u32 s4, s4, s9
	s_addc_u32 s5, s5, 0
	global_load_dwordx2 v[134:135], v136, s[4:5]
	global_load_dwordx2 v[204:205], v136, s[4:5] offset:512
	ds_write_b128 v128, v[124:127] offset:0
	ds_write_b128 v128, v[120:123] offset:16
	ds_write_b128 v128, v[116:119] offset:8448
	ds_write_b128 v128, v[112:115] offset:8464
	ds_write_b128 v128, v[100:103] offset:16896
	ds_write_b128 v128, v[96:99] offset:16912
	ds_write_b128 v128, v[84:87] offset:25344
	ds_write_b128 v128, v[80:83] offset:25360
	ds_write_b128 v129, v[60:63] offset:0
	ds_write_b128 v129, v[56:59] offset:16
	ds_write_b128 v129, v[52:55] offset:8448
	ds_write_b128 v129, v[48:51] offset:8464
	ds_write_b128 v129, v[36:39] offset:16896
	ds_write_b128 v129, v[32:35] offset:16912
	ds_write_b128 v129, v[20:23] offset:25344
	ds_write_b128 v129, v[16:19] offset:25360
	s_waitcnt lgkmcnt(0)
	s_barrier
	v_readfirstlane_b32 s8, v234
	s_nop 1
	s_cmpk_gt_u32 s8, 0xff
	s_cbranch_scc1 .Ls1f_scan_done_0
	s_waitcnt vmcnt(0)
	v_mov_b32_e32 v136, 0
	v_mov_b32_e32 v137, 0
	ds_read_b32 v140, v130 offset:0
	ds_read_b32 v141, v130 offset:256
	ds_read_b32 v142, v130 offset:528
	ds_read_b32 v143, v130 offset:784
	ds_read_b32 v144, v130 offset:1056
	ds_read_b32 v145, v130 offset:1312
	ds_read_b32 v146, v130 offset:1584
	ds_read_b32 v147, v130 offset:1840
	ds_read_b32 v148, v130 offset:2112
	ds_read_b32 v149, v130 offset:2368
	ds_read_b32 v150, v130 offset:2640
	ds_read_b32 v151, v130 offset:2896
	ds_read_b32 v152, v130 offset:3168
	ds_read_b32 v153, v130 offset:3424
	ds_read_b32 v154, v130 offset:3696
	ds_read_b32 v155, v130 offset:3952
	ds_read_b32 v156, v130 offset:4224
	ds_read_b32 v157, v130 offset:4480
	ds_read_b32 v158, v130 offset:4752
	ds_read_b32 v159, v130 offset:5008
	ds_read_b32 v160, v130 offset:5280
	ds_read_b32 v161, v130 offset:5536
	ds_read_b32 v162, v130 offset:5808
	ds_read_b32 v163, v130 offset:6064
	ds_read_b32 v164, v130 offset:6336
	ds_read_b32 v165, v130 offset:6592
	ds_read_b32 v166, v130 offset:6864
	ds_read_b32 v167, v130 offset:7120
	ds_read_b32 v168, v130 offset:7392
	ds_read_b32 v169, v130 offset:7648
	ds_read_b32 v170, v130 offset:7920
	ds_read_b32 v171, v130 offset:8176
	ds_read_b32 v172, v130 offset:8448
	ds_read_b32 v173, v130 offset:8704
	ds_read_b32 v174, v130 offset:8976
	ds_read_b32 v175, v130 offset:9232
	ds_read_b32 v176, v130 offset:9504
	ds_read_b32 v177, v130 offset:9760
	ds_read_b32 v178, v130 offset:10032
	ds_read_b32 v179, v130 offset:10288
	ds_read_b32 v180, v130 offset:10560
	ds_read_b32 v181, v130 offset:10816
	ds_read_b32 v182, v130 offset:11088
	ds_read_b32 v183, v130 offset:11344
	ds_read_b32 v184, v130 offset:11616
	ds_read_b32 v185, v130 offset:11872
	ds_read_b32 v186, v130 offset:12144
	ds_read_b32 v187, v130 offset:12400
	ds_read_b32 v188, v130 offset:12672
	ds_read_b32 v189, v130 offset:12928
	ds_read_b32 v190, v130 offset:13200
	ds_read_b32 v191, v130 offset:13456
	ds_read_b32 v192, v130 offset:13728
	ds_read_b32 v193, v130 offset:13984
	ds_read_b32 v194, v130 offset:14256
	ds_read_b32 v195, v130 offset:14512
	ds_read_b32 v196, v130 offset:14784
	ds_read_b32 v197, v130 offset:15040
	ds_read_b32 v198, v130 offset:15312
	ds_read_b32 v199, v130 offset:15568
	ds_read_b32 v200, v130 offset:15840
	ds_read_b32 v201, v130 offset:16096
	ds_read_b32 v202, v130 offset:16368
	ds_read_b32 v203, v130 offset:16624
	s_waitcnt lgkmcnt(0)
; __device__ __forceinline__ unsigned f2bf(float f) { unsigned u = __builtin_bit_cast(unsigned, f); return (u + 0x7fffu + ((u >> 16) & 1u)) >> 16; }
; __device__ __forceinline__ void s2_phase(const float* SBUF, bf16_t* ACOMB, const float* lamT, int bx, int tid) {
;     ...
;     for (int blk = 0; blk < 2; ++blk) {
;         float sr[32], si[32];
; #pragma unroll
;         for (int k = 0; k < 32; ++k) { const int c = (d == 0) ? (blk * 32 + k) : (63 - (blk * 32 + k)); sr[k] = sp[(size_t)c * 256]; si[k] = sp[(size_t)c * 256 + 64]; }
; #pragma unroll
;         for (int k = 0; k < 32; ++k) { const int c = (d == 0) ? (blk * 32 + k) : (63 - (blk * 32 + k));
;             xp[(size_t)c * KA] = (bf16_t)f2bf(xr); xp[(size_t)c * KA + 64] = (bf16_t)f2bf(xi);
;             const float nr = lr * xr - li * xi + sr[k], ni = lr * xi + li * xr + si[k]; xr = nr; xi = ni; }
	ds_write_b32 v130, v136 offset:0
	ds_write_b32 v130, v137 offset:256
	v_fma_f32 v138, v134, v136, v140
	v_fma_f32 v139, v134, v137, v141
	v_fma_f32 v138, -v135, v137, v138
	v_fma_f32 v139, v135, v136, v139
	ds_write_b32 v130, v138 offset:528
	ds_write_b32 v130, v139 offset:784
	v_fma_f32 v136, v134, v138, v142
	v_fma_f32 v137, v134, v139, v143
	v_fma_f32 v136, -v135, v139, v136
	v_fma_f32 v137, v135, v138, v137
	ds_write_b32 v130, v136 offset:1056
	ds_write_b32 v130, v137 offset:1312
	v_fma_f32 v138, v134, v136, v144
	v_fma_f32 v139, v134, v137, v145
	v_fma_f32 v138, -v135, v137, v138
	v_fma_f32 v139, v135, v136, v139
	ds_write_b32 v130, v138 offset:1584
	ds_write_b32 v130, v139 offset:1840
	v_fma_f32 v136, v134, v138, v146
	v_fma_f32 v137, v134, v139, v147
	v_fma_f32 v136, -v135, v139, v136
	v_fma_f32 v137, v135, v138, v137
	ds_write_b32 v130, v136 offset:2112
	ds_write_b32 v130, v137 offset:2368
	v_fma_f32 v138, v134, v136, v148
	v_fma_f32 v139, v134, v137, v149
	v_fma_f32 v138, -v135, v137, v138
	v_fma_f32 v139, v135, v136, v139
	ds_write_b32 v130, v138 offset:2640
	ds_write_b32 v130, v139 offset:2896
	v_fma_f32 v136, v134, v138, v150
	v_fma_f32 v137, v134, v139, v151
	v_fma_f32 v136, -v135, v139, v136
	v_fma_f32 v137, v135, v138, v137
	ds_write_b32 v130, v136 offset:3168
	ds_write_b32 v130, v137 offset:3424
	v_fma_f32 v138, v134, v136, v152
	v_fma_f32 v139, v134, v137, v153
	v_fma_f32 v138, -v135, v137, v138
	v_fma_f32 v139, v135, v136, v139
	ds_write_b32 v130, v138 offset:3696
	ds_write_b32 v130, v139 offset:3952
	v_fma_f32 v136, v134, v138, v154
	v_fma_f32 v137, v134, v139, v155
	v_fma_f32 v136, -v135, v139, v136
	v_fma_f32 v137, v135, v138, v137
	ds_write_b32 v130, v136 offset:4224
	ds_write_b32 v130, v137 offset:4480
	v_fma_f32 v138, v134, v136, v156
	v_fma_f32 v139, v134, v137, v157
	v_fma_f32 v138, -v135, v137, v138
	v_fma_f32 v139, v135, v136, v139
	ds_write_b32 v130, v138 offset:4752
	ds_write_b32 v130, v139 offset:5008
	v_fma_f32 v136, v134, v138, v158
	v_fma_f32 v137, v134, v139, v159
	v_fma_f32 v136, -v135, v139, v136
	v_fma_f32 v137, v135, v138, v137
	ds_write_b32 v130, v136 offset:5280
	ds_write_b32 v130, v137 offset:5536
	v_fma_f32 v138, v134, v136, v160
	v_fma_f32 v139, v134, v137, v161
	v_fma_f32 v138, -v135, v137, v138
	v_fma_f32 v139, v135, v136, v139
	ds_write_b32 v130, v138 offset:5808
	ds_write_b32 v130, v139 offset:6064
	v_fma_f32 v136, v134, v138, v162
	v_fma_f32 v137, v134, v139, v163
	v_fma_f32 v136, -v135, v139, v136
	v_fma_f32 v137, v135, v138, v137
	ds_write_b32 v130, v136 offset:6336
	ds_write_b32 v130, v137 offset:6592
	v_fma_f32 v138, v134, v136, v164
	v_fma_f32 v139, v134, v137, v165
	v_fma_f32 v138, -v135, v137, v138
	v_fma_f32 v139, v135, v136, v139
	ds_write_b32 v130, v138 offset:6864
	ds_write_b32 v130, v139 offset:7120
	v_fma_f32 v136, v134, v138, v166
	v_fma_f32 v137, v134, v139, v167
	v_fma_f32 v136, -v135, v139, v136
	v_fma_f32 v137, v135, v138, v137
	ds_write_b32 v130, v136 offset:7392
	ds_write_b32 v130, v137 offset:7648
	v_fma_f32 v138, v134, v136, v168
	v_fma_f32 v139, v134, v137, v169
	v_fma_f32 v138, -v135, v137, v138
	v_fma_f32 v139, v135, v136, v139
	ds_write_b32 v130, v138 offset:7920
	ds_write_b32 v130, v139 offset:8176
	v_fma_f32 v136, v134, v138, v170
	v_fma_f32 v137, v134, v139, v171
	v_fma_f32 v136, -v135, v139, v136
	v_fma_f32 v137, v135, v138, v137
	ds_write_b32 v130, v136 offset:8448
	ds_write_b32 v130, v137 offset:8704
	v_fma_f32 v138, v134, v136, v172
	v_fma_f32 v139, v134, v137, v173
	v_fma_f32 v138, -v135, v137, v138
	v_fma_f32 v139, v135, v136, v139
	ds_write_b32 v130, v138 offset:8976
	ds_write_b32 v130, v139 offset:9232
	v_fma_f32 v136, v134, v138, v174
	v_fma_f32 v137, v134, v139, v175
	v_fma_f32 v136, -v135, v139, v136
	v_fma_f32 v137, v135, v138, v137
	ds_write_b32 v130, v136 offset:9504
	ds_write_b32 v130, v137 offset:9760
	v_fma_f32 v138, v134, v136, v176
	v_fma_f32 v139, v134, v137, v177
	v_fma_f32 v138, -v135, v137, v138
	v_fma_f32 v139, v135, v136, v139
	ds_write_b32 v130, v138 offset:10032
	ds_write_b32 v130, v139 offset:10288
	v_fma_f32 v136, v134, v138, v178
	v_fma_f32 v137, v134, v139, v179
	v_fma_f32 v136, -v135, v139, v136
	v_fma_f32 v137, v135, v138, v137
	ds_write_b32 v130, v136 offset:10560
	ds_write_b32 v130, v137 offset:10816
	v_fma_f32 v138, v134, v136, v180
	v_fma_f32 v139, v134, v137, v181
	v_fma_f32 v138, -v135, v137, v138
	v_fma_f32 v139, v135, v136, v139
	ds_write_b32 v130, v138 offset:11088
	ds_write_b32 v130, v139 offset:11344
	v_fma_f32 v136, v134, v138, v182
	v_fma_f32 v137, v134, v139, v183
	v_fma_f32 v136, -v135, v139, v136
	v_fma_f32 v137, v135, v138, v137
	ds_write_b32 v130, v136 offset:11616
	ds_write_b32 v130, v137 offset:11872
	v_fma_f32 v138, v134, v136, v184
	v_fma_f32 v139, v134, v137, v185
	v_fma_f32 v138, -v135, v137, v138
	v_fma_f32 v139, v135, v136, v139
	ds_write_b32 v130, v138 offset:12144
	ds_write_b32 v130, v139 offset:12400
	v_fma_f32 v136, v134, v138, v186
	v_fma_f32 v137, v134, v139, v187
	v_fma_f32 v136, -v135, v139, v136
	v_fma_f32 v137, v135, v138, v137
	ds_write_b32 v130, v136 offset:12672
	ds_write_b32 v130, v137 offset:12928
	v_fma_f32 v138, v134, v136, v188
	v_fma_f32 v139, v134, v137, v189
	v_fma_f32 v138, -v135, v137, v138
	v_fma_f32 v139, v135, v136, v139
	ds_write_b32 v130, v138 offset:13200
	ds_write_b32 v130, v139 offset:13456
	v_fma_f32 v136, v134, v138, v190
	v_fma_f32 v137, v134, v139, v191
	v_fma_f32 v136, -v135, v139, v136
	v_fma_f32 v137, v135, v138, v137
	ds_write_b32 v130, v136 offset:13728
	ds_write_b32 v130, v137 offset:13984
	v_fma_f32 v138, v134, v136, v192
	v_fma_f32 v139, v134, v137, v193
; __device__ __forceinline__ unsigned f2bf(float f) { unsigned u = __builtin_bit_cast(unsigned, f); return (u + 0x7fffu + ((u >> 16) & 1u)) >> 16; }
; __device__ __forceinline__ void s2_phase(const float* SBUF, bf16_t* ACOMB, const float* lamT, int bx, int tid) {
;     ...
;     for (int blk = 0; blk < 2; ++blk) {
;         float sr[32], si[32];
; #pragma unroll
;         for (int k = 0; k < 32; ++k) { const int c = (d == 0) ? (blk * 32 + k) : (63 - (blk * 32 + k)); sr[k] = sp[(size_t)c * 256]; si[k] = sp[(size_t)c * 256 + 64]; }
; #pragma unroll
;         for (int k = 0; k < 32; ++k) { const int c = (d == 0) ? (blk * 32 + k) : (63 - (blk * 32 + k));
;             xp[(size_t)c * KA] = (bf16_t)f2bf(xr); xp[(size_t)c * KA + 64] = (bf16_t)f2bf(xi);
;             const float nr = lr * xr - li * xi + sr[k], ni = lr * xi + li * xr + si[k]; xr = nr; xi = ni; }
	v_fma_f32 v138, -v135, v137, v138
	v_fma_f32 v139, v135, v136, v139
	ds_write_b32 v130, v138 offset:14256
	ds_write_b32 v130, v139 offset:14512
	v_fma_f32 v136, v134, v138, v194
	v_fma_f32 v137, v134, v139, v195
	v_fma_f32 v136, -v135, v139, v136
	v_fma_f32 v137, v135, v138, v137
	ds_write_b32 v130, v136 offset:14784
	ds_write_b32 v130, v137 offset:15040
	v_fma_f32 v138, v134, v136, v196
	v_fma_f32 v139, v134, v137, v197
	v_fma_f32 v138, -v135, v137, v138
	v_fma_f32 v139, v135, v136, v139
	ds_write_b32 v130, v138 offset:15312
	ds_write_b32 v130, v139 offset:15568
	v_fma_f32 v136, v134, v138, v198
	v_fma_f32 v137, v134, v139, v199
	v_fma_f32 v136, -v135, v139, v136
	v_fma_f32 v137, v135, v138, v137
	ds_write_b32 v130, v136 offset:15840
	ds_write_b32 v130, v137 offset:16096
	v_fma_f32 v138, v134, v136, v200
	v_fma_f32 v139, v134, v137, v201
	v_fma_f32 v138, -v135, v137, v138
	v_fma_f32 v139, v135, v136, v139
	ds_write_b32 v130, v138 offset:16368
	ds_write_b32 v130, v139 offset:16624
	v_fma_f32 v136, v134, v138, v202
	v_fma_f32 v137, v134, v139, v203
	v_fma_f32 v136, -v135, v139, v136
	v_fma_f32 v137, v135, v138, v137
	ds_read_b32 v140, v130 offset:16896
	ds_read_b32 v141, v130 offset:17152
	ds_read_b32 v142, v130 offset:17424
	ds_read_b32 v143, v130 offset:17680
	ds_read_b32 v144, v130 offset:17952
	ds_read_b32 v145, v130 offset:18208
	ds_read_b32 v146, v130 offset:18480
	ds_read_b32 v147, v130 offset:18736
	ds_read_b32 v148, v130 offset:19008
	ds_read_b32 v149, v130 offset:19264
	ds_read_b32 v150, v130 offset:19536
	ds_read_b32 v151, v130 offset:19792
	ds_read_b32 v152, v130 offset:20064
	ds_read_b32 v153, v130 offset:20320
	ds_read_b32 v154, v130 offset:20592
	ds_read_b32 v155, v130 offset:20848
	ds_read_b32 v156, v130 offset:21120
	ds_read_b32 v157, v130 offset:21376
	ds_read_b32 v158, v130 offset:21648
	ds_read_b32 v159, v130 offset:21904
	ds_read_b32 v160, v130 offset:22176
	ds_read_b32 v161, v130 offset:22432
	ds_read_b32 v162, v130 offset:22704
	ds_read_b32 v163, v130 offset:22960
	ds_read_b32 v164, v130 offset:23232
	ds_read_b32 v165, v130 offset:23488
	ds_read_b32 v166, v130 offset:23760
	ds_read_b32 v167, v130 offset:24016
	ds_read_b32 v168, v130 offset:24288
	ds_read_b32 v169, v130 offset:24544
	ds_read_b32 v170, v130 offset:24816
	ds_read_b32 v171, v130 offset:25072
	ds_read_b32 v172, v130 offset:25344
	ds_read_b32 v173, v130 offset:25600
	ds_read_b32 v174, v130 offset:25872
	ds_read_b32 v175, v130 offset:26128
	ds_read_b32 v176, v130 offset:26400
	ds_read_b32 v177, v130 offset:26656
	ds_read_b32 v178, v130 offset:26928
	ds_read_b32 v179, v130 offset:27184
	ds_read_b32 v180, v130 offset:27456
	ds_read_b32 v181, v130 offset:27712
	ds_read_b32 v182, v130 offset:27984
	ds_read_b32 v183, v130 offset:28240
	ds_read_b32 v184, v130 offset:28512
	ds_read_b32 v185, v130 offset:28768
	ds_read_b32 v186, v130 offset:29040
	ds_read_b32 v187, v130 offset:29296
	ds_read_b32 v188, v130 offset:29568
	ds_read_b32 v189, v130 offset:29824
	ds_read_b32 v190, v130 offset:30096
	ds_read_b32 v191, v130 offset:30352
	ds_read_b32 v192, v130 offset:30624
	ds_read_b32 v193, v130 offset:30880
	ds_read_b32 v194, v130 offset:31152
	ds_read_b32 v195, v130 offset:31408
	ds_read_b32 v196, v130 offset:31680
	ds_read_b32 v197, v130 offset:31936
	ds_read_b32 v198, v130 offset:32208
	ds_read_b32 v199, v130 offset:32464
	ds_read_b32 v200, v130 offset:32736
	ds_read_b32 v201, v130 offset:32992
	ds_read_b32 v202, v130 offset:33264
	ds_read_b32 v203, v130 offset:33520
	s_waitcnt lgkmcnt(0)
	ds_write_b32 v130, v136 offset:16896
	ds_write_b32 v130, v137 offset:17152
	v_fma_f32 v138, v134, v136, v140
	v_fma_f32 v139, v134, v137, v141
	v_fma_f32 v138, -v135, v137, v138
	v_fma_f32 v139, v135, v136, v139
	ds_write_b32 v130, v138 offset:17424
	ds_write_b32 v130, v139 offset:17680
	v_fma_f32 v136, v134, v138, v142
	v_fma_f32 v137, v134, v139, v143
	v_fma_f32 v136, -v135, v139, v136
	v_fma_f32 v137, v135, v138, v137
	ds_write_b32 v130, v136 offset:17952
	ds_write_b32 v130, v137 offset:18208
	v_fma_f32 v138, v134, v136, v144
	v_fma_f32 v139, v134, v137, v145
	v_fma_f32 v138, -v135, v137, v138
	v_fma_f32 v139, v135, v136, v139
	ds_write_b32 v130, v138 offset:18480
	ds_write_b32 v130, v139 offset:18736
	v_fma_f32 v136, v134, v138, v146
	v_fma_f32 v137, v134, v139, v147
	v_fma_f32 v136, -v135, v139, v136
	v_fma_f32 v137, v135, v138, v137
	ds_write_b32 v130, v136 offset:19008
	ds_write_b32 v130, v137 offset:19264
	v_fma_f32 v138, v134, v136, v148
	v_fma_f32 v139, v134, v137, v149
	v_fma_f32 v138, -v135, v137, v138
	v_fma_f32 v139, v135, v136, v139
	ds_write_b32 v130, v138 offset:19536
	ds_write_b32 v130, v139 offset:19792
	v_fma_f32 v136, v134, v138, v150
	v_fma_f32 v137, v134, v139, v151
	v_fma_f32 v136, -v135, v139, v136
	v_fma_f32 v137, v135, v138, v137
	ds_write_b32 v130, v136 offset:20064
	ds_write_b32 v130, v137 offset:20320
	v_fma_f32 v138, v134, v136, v152
	v_fma_f32 v139, v134, v137, v153
	v_fma_f32 v138, -v135, v137, v138
	v_fma_f32 v139, v135, v136, v139
	ds_write_b32 v130, v138 offset:20592
	ds_write_b32 v130, v139 offset:20848
	v_fma_f32 v136, v134, v138, v154
	v_fma_f32 v137, v134, v139, v155
	v_fma_f32 v136, -v135, v139, v136
	v_fma_f32 v137, v135, v138, v137
	ds_write_b32 v130, v136 offset:21120
	ds_write_b32 v130, v137 offset:21376
	v_fma_f32 v138, v134, v136, v156
	v_fma_f32 v139, v134, v137, v157
	v_fma_f32 v138, -v135, v137, v138
	v_fma_f32 v139, v135, v136, v139
	ds_write_b32 v130, v138 offset:21648
	ds_write_b32 v130, v139 offset:21904
	v_fma_f32 v136, v134, v138, v158
	v_fma_f32 v137, v134, v139, v159
	v_fma_f32 v136, -v135, v139, v136
	v_fma_f32 v137, v135, v138, v137
; __device__ __forceinline__ unsigned f2bf(float f) { unsigned u = __builtin_bit_cast(unsigned, f); return (u + 0x7fffu + ((u >> 16) & 1u)) >> 16; }
; __device__ __forceinline__ void s2_phase(const float* SBUF, bf16_t* ACOMB, const float* lamT, int bx, int tid) {
;     ...
;     for (int blk = 0; blk < 2; ++blk) {
;         float sr[32], si[32];
; #pragma unroll
;         for (int k = 0; k < 32; ++k) { const int c = (d == 0) ? (blk * 32 + k) : (63 - (blk * 32 + k)); sr[k] = sp[(size_t)c * 256]; si[k] = sp[(size_t)c * 256 + 64]; }
; #pragma unroll
;         for (int k = 0; k < 32; ++k) { const int c = (d == 0) ? (blk * 32 + k) : (63 - (blk * 32 + k));
;             xp[(size_t)c * KA] = (bf16_t)f2bf(xr); xp[(size_t)c * KA + 64] = (bf16_t)f2bf(xi);
;             const float nr = lr * xr - li * xi + sr[k], ni = lr * xi + li * xr + si[k]; xr = nr; xi = ni; }
	ds_write_b32 v130, v136 offset:22176
	ds_write_b32 v130, v137 offset:22432
	v_fma_f32 v138, v134, v136, v160
	v_fma_f32 v139, v134, v137, v161
	v_fma_f32 v138, -v135, v137, v138
	v_fma_f32 v139, v135, v136, v139
	ds_write_b32 v130, v138 offset:22704
	ds_write_b32 v130, v139 offset:22960
	v_fma_f32 v136, v134, v138, v162
	v_fma_f32 v137, v134, v139, v163
	v_fma_f32 v136, -v135, v139, v136
	v_fma_f32 v137, v135, v138, v137
	ds_write_b32 v130, v136 offset:23232
	ds_write_b32 v130, v137 offset:23488
	v_fma_f32 v138, v134, v136, v164
	v_fma_f32 v139, v134, v137, v165
	v_fma_f32 v138, -v135, v137, v138
	v_fma_f32 v139, v135, v136, v139
	ds_write_b32 v130, v138 offset:23760
	ds_write_b32 v130, v139 offset:24016
	v_fma_f32 v136, v134, v138, v166
	v_fma_f32 v137, v134, v139, v167
	v_fma_f32 v136, -v135, v139, v136
	v_fma_f32 v137, v135, v138, v137
	ds_write_b32 v130, v136 offset:24288
	ds_write_b32 v130, v137 offset:24544
	v_fma_f32 v138, v134, v136, v168
	v_fma_f32 v139, v134, v137, v169
	v_fma_f32 v138, -v135, v137, v138
	v_fma_f32 v139, v135, v136, v139
	ds_write_b32 v130, v138 offset:24816
	ds_write_b32 v130, v139 offset:25072
	v_fma_f32 v136, v134, v138, v170
	v_fma_f32 v137, v134, v139, v171
	v_fma_f32 v136, -v135, v139, v136
	v_fma_f32 v137, v135, v138, v137
	ds_write_b32 v130, v136 offset:25344
	ds_write_b32 v130, v137 offset:25600
	v_fma_f32 v138, v134, v136, v172
	v_fma_f32 v139, v134, v137, v173
	v_fma_f32 v138, -v135, v137, v138
	v_fma_f32 v139, v135, v136, v139
	ds_write_b32 v130, v138 offset:25872
	ds_write_b32 v130, v139 offset:26128
	v_fma_f32 v136, v134, v138, v174
	v_fma_f32 v137, v134, v139, v175
	v_fma_f32 v136, -v135, v139, v136
	v_fma_f32 v137, v135, v138, v137
	ds_write_b32 v130, v136 offset:26400
	ds_write_b32 v130, v137 offset:26656
	v_fma_f32 v138, v134, v136, v176
	v_fma_f32 v139, v134, v137, v177
	v_fma_f32 v138, -v135, v137, v138
	v_fma_f32 v139, v135, v136, v139
	ds_write_b32 v130, v138 offset:26928
	ds_write_b32 v130, v139 offset:27184
	v_fma_f32 v136, v134, v138, v178
	v_fma_f32 v137, v134, v139, v179
	v_fma_f32 v136, -v135, v139, v136
	v_fma_f32 v137, v135, v138, v137
	ds_write_b32 v130, v136 offset:27456
	ds_write_b32 v130, v137 offset:27712
	v_fma_f32 v138, v134, v136, v180
	v_fma_f32 v139, v134, v137, v181
	v_fma_f32 v138, -v135, v137, v138
	v_fma_f32 v139, v135, v136, v139
	ds_write_b32 v130, v138 offset:27984
	ds_write_b32 v130, v139 offset:28240
	v_fma_f32 v136, v134, v138, v182
	v_fma_f32 v137, v134, v139, v183
	v_fma_f32 v136, -v135, v139, v136
	v_fma_f32 v137, v135, v138, v137
	ds_write_b32 v130, v136 offset:28512
	ds_write_b32 v130, v137 offset:28768
	v_fma_f32 v138, v134, v136, v184
	v_fma_f32 v139, v134, v137, v185
	v_fma_f32 v138, -v135, v137, v138
	v_fma_f32 v139, v135, v136, v139
	ds_write_b32 v130, v138 offset:29040
	ds_write_b32 v130, v139 offset:29296
	v_fma_f32 v136, v134, v138, v186
	v_fma_f32 v137, v134, v139, v187
	v_fma_f32 v136, -v135, v139, v136
	v_fma_f32 v137, v135, v138, v137
	ds_write_b32 v130, v136 offset:29568
	ds_write_b32 v130, v137 offset:29824
	v_fma_f32 v138, v134, v136, v188
	v_fma_f32 v139, v134, v137, v189
	v_fma_f32 v138, -v135, v137, v138
	v_fma_f32 v139, v135, v136, v139
	ds_write_b32 v130, v138 offset:30096
	ds_write_b32 v130, v139 offset:30352
	v_fma_f32 v136, v134, v138, v190
	v_fma_f32 v137, v134, v139, v191
	v_fma_f32 v136, -v135, v139, v136
	v_fma_f32 v137, v135, v138, v137
	ds_write_b32 v130, v136 offset:30624
	ds_write_b32 v130, v137 offset:30880
	v_fma_f32 v138, v134, v136, v192
	v_fma_f32 v139, v134, v137, v193
	v_fma_f32 v138, -v135, v137, v138
	v_fma_f32 v139, v135, v136, v139
	ds_write_b32 v130, v138 offset:31152
	ds_write_b32 v130, v139 offset:31408
	v_fma_f32 v136, v134, v138, v194
	v_fma_f32 v137, v134, v139, v195
	v_fma_f32 v136, -v135, v139, v136
	v_fma_f32 v137, v135, v138, v137
	ds_write_b32 v130, v136 offset:31680
	ds_write_b32 v130, v137 offset:31936
	v_fma_f32 v138, v134, v136, v196
	v_fma_f32 v139, v134, v137, v197
	v_fma_f32 v138, -v135, v137, v138
	v_fma_f32 v139, v135, v136, v139
	ds_write_b32 v130, v138 offset:32208
	ds_write_b32 v130, v139 offset:32464
	v_fma_f32 v136, v134, v138, v198
	v_fma_f32 v137, v134, v139, v199
	v_fma_f32 v136, -v135, v139, v136
	v_fma_f32 v137, v135, v138, v137
	ds_write_b32 v130, v136 offset:32736
	ds_write_b32 v130, v137 offset:32992
	v_fma_f32 v138, v134, v136, v200
	v_fma_f32 v139, v134, v137, v201
	v_fma_f32 v138, -v135, v137, v138
	v_fma_f32 v139, v135, v136, v139
	ds_write_b32 v130, v138 offset:33264
	ds_write_b32 v130, v139 offset:33520
	v_fma_f32 v136, v134, v138, v202
	v_fma_f32 v137, v134, v139, v203
	v_fma_f32 v136, -v135, v139, v136
	v_fma_f32 v137, v135, v138, v137
; __device__ __forceinline__ unsigned f2bf(float f) { unsigned u = __builtin_bit_cast(unsigned, f); return (u + 0x7fffu + ((u >> 16) & 1u)) >> 16; }
; __device__ __forceinline__ void s2_phase(const float* SBUF, bf16_t* ACOMB, const float* lamT, int bx, int tid) {
;     ...
;         for (int k = 0; k < 32; ++k) { const int c = (d == 0) ? (blk * 32 + k) : (63 - (blk * 32 + k)); sr[k] = sp[(size_t)c * 256]; si[k] = sp[(size_t)c * 256 + 64]; }
; #pragma unroll
;         for (int k = 0; k < 32; ++k) { const int c = (d == 0) ? (blk * 32 + k) : (63 - (blk * 32 + k));
;             xp[(size_t)c * KA] = (bf16_t)f2bf(xr); xp[(size_t)c * KA + 64] = (bf16_t)f2bf(xi);
;             const float nr = lr * xr - li * xi + sr[k], ni = lr * xi + li * xr + si[k]; xr = nr; xi = ni; }
.Ls1f_scan_done_0:
	s_waitcnt lgkmcnt(0)
	s_barrier
	ds_read_b128 v[140:143], v131 offset:0
	ds_read_b128 v[144:147], v131 offset:16
	ds_read_b128 v[148:151], v131 offset:16896
	ds_read_b128 v[152:155], v131 offset:16912
	ds_read_b128 v[156:159], v131 offset:33792
	ds_read_b128 v[160:163], v131 offset:33808
	ds_read_b128 v[164:167], v131 offset:50688
	ds_read_b128 v[168:171], v131 offset:50704
	ds_read_b128 v[172:175], v132 offset:0
	ds_read_b128 v[176:179], v132 offset:16
	ds_read_b128 v[180:183], v132 offset:16896
	ds_read_b128 v[184:187], v132 offset:16912
	ds_read_b128 v[188:191], v132 offset:33792
	ds_read_b128 v[192:195], v132 offset:33808
	ds_read_b128 v[196:199], v132 offset:50688
	ds_read_b128 v[200:203], v132 offset:50704
	s_waitcnt lgkmcnt(14)
	v_cvt_pk_bf16_f32 v140, v140, v141
	v_cvt_pk_bf16_f32 v141, v142, v143
	v_cvt_pk_bf16_f32 v142, v144, v145
	v_cvt_pk_bf16_f32 v143, v146, v147
	v_mov_b32_e32 v206, v133
	global_store_dwordx4 v206, v[140:143], s[6:7] offset:0
	s_waitcnt lgkmcnt(12)
	v_cvt_pk_bf16_f32 v148, v148, v149
	v_cvt_pk_bf16_f32 v149, v150, v151
	v_cvt_pk_bf16_f32 v150, v152, v153
	v_cvt_pk_bf16_f32 v151, v154, v155
	v_add_u32_e32 v207, 0xc000, v133
	global_store_dwordx4 v207, v[148:151], s[6:7] offset:0
	s_waitcnt lgkmcnt(10)
	v_cvt_pk_bf16_f32 v156, v156, v157
	v_cvt_pk_bf16_f32 v157, v158, v159
	v_cvt_pk_bf16_f32 v158, v160, v161
	v_cvt_pk_bf16_f32 v159, v162, v163
	v_add_u32_e32 v208, 0x18000, v133
	global_store_dwordx4 v208, v[156:159], s[6:7] offset:0
	s_waitcnt lgkmcnt(8)
	v_cvt_pk_bf16_f32 v164, v164, v165
	v_cvt_pk_bf16_f32 v165, v166, v167
	v_cvt_pk_bf16_f32 v166, v168, v169
	v_cvt_pk_bf16_f32 v167, v170, v171
	v_add_u32_e32 v209, 0x24000, v133
	global_store_dwordx4 v209, v[164:167], s[6:7] offset:0
	s_waitcnt lgkmcnt(6)
	v_cvt_pk_bf16_f32 v172, v172, v173
	v_cvt_pk_bf16_f32 v173, v174, v175
	v_cvt_pk_bf16_f32 v174, v176, v177
	v_cvt_pk_bf16_f32 v175, v178, v179
	v_add_u32_e32 v210, 0x30000, v133
	global_store_dwordx4 v210, v[172:175], s[6:7] offset:0
	s_waitcnt lgkmcnt(4)
	v_cvt_pk_bf16_f32 v180, v180, v181
	v_cvt_pk_bf16_f32 v181, v182, v183
	v_cvt_pk_bf16_f32 v182, v184, v185
	v_cvt_pk_bf16_f32 v183, v186, v187
	v_add_u32_e32 v211, 0x3c000, v133
	global_store_dwordx4 v211, v[180:183], s[6:7] offset:0
	s_waitcnt lgkmcnt(2)
	v_cvt_pk_bf16_f32 v188, v188, v189
	v_cvt_pk_bf16_f32 v189, v190, v191
	v_cvt_pk_bf16_f32 v190, v192, v193
	v_cvt_pk_bf16_f32 v191, v194, v195
	v_add_u32_e32 v212, 0x48000, v133
	global_store_dwordx4 v212, v[188:191], s[6:7] offset:0
	s_waitcnt lgkmcnt(0)
	v_cvt_pk_bf16_f32 v196, v196, v197
	v_cvt_pk_bf16_f32 v197, v198, v199
	v_cvt_pk_bf16_f32 v198, v200, v201
	v_cvt_pk_bf16_f32 v199, v202, v203
	v_add_u32_e32 v213, 0x54000, v133
	global_store_dwordx4 v213, v[196:199], s[6:7] offset:0
	s_barrier
	ds_write_b128 v128, v[108:111] offset:0
	ds_write_b128 v128, v[104:107] offset:16
	ds_write_b128 v128, v[92:95] offset:8448
	ds_write_b128 v128, v[88:91] offset:8464
	ds_write_b128 v128, v[76:79] offset:16896
	ds_write_b128 v128, v[72:75] offset:16912
	ds_write_b128 v128, v[68:71] offset:25344
	ds_write_b128 v128, v[64:67] offset:25360
	ds_write_b128 v129, v[44:47] offset:0
	ds_write_b128 v129, v[40:43] offset:16
	ds_write_b128 v129, v[28:31] offset:8448
	ds_write_b128 v129, v[24:27] offset:8464
	ds_write_b128 v129, v[12:15] offset:16896
	ds_write_b128 v129, v[8:11] offset:16912
	ds_write_b128 v129, v[4:7] offset:25344
	ds_write_b128 v129, v[0:3] offset:25360
	s_waitcnt lgkmcnt(0)
	s_barrier
	v_readfirstlane_b32 s8, v234
	s_nop 1
	s_cmpk_gt_u32 s8, 0xff
	s_cbranch_scc1 .Ls1f_scan_done_1
	v_mov_b32_e32 v136, 0
	v_mov_b32_e32 v137, 0
	ds_read_b32 v140, v130 offset:33264
	ds_read_b32 v141, v130 offset:33520
	ds_read_b32 v142, v130 offset:32736
	ds_read_b32 v143, v130 offset:32992
	ds_read_b32 v144, v130 offset:32208
	ds_read_b32 v145, v130 offset:32464
	ds_read_b32 v146, v130 offset:31680
	ds_read_b32 v147, v130 offset:31936
	ds_read_b32 v148, v130 offset:31152
	ds_read_b32 v149, v130 offset:31408
	ds_read_b32 v150, v130 offset:30624
	ds_read_b32 v151, v130 offset:30880
	ds_read_b32 v152, v130 offset:30096
	ds_read_b32 v153, v130 offset:30352
	ds_read_b32 v154, v130 offset:29568
	ds_read_b32 v155, v130 offset:29824
	ds_read_b32 v156, v130 offset:29040
	ds_read_b32 v157, v130 offset:29296
	ds_read_b32 v158, v130 offset:28512
	ds_read_b32 v159, v130 offset:28768
	ds_read_b32 v160, v130 offset:27984
	ds_read_b32 v161, v130 offset:28240
	ds_read_b32 v162, v130 offset:27456
	ds_read_b32 v163, v130 offset:27712
	ds_read_b32 v164, v130 offset:26928
	ds_read_b32 v165, v130 offset:27184
	ds_read_b32 v166, v130 offset:26400
	ds_read_b32 v167, v130 offset:26656
	ds_read_b32 v168, v130 offset:25872
	ds_read_b32 v169, v130 offset:26128
	ds_read_b32 v170, v130 offset:25344
	ds_read_b32 v171, v130 offset:25600
	ds_read_b32 v172, v130 offset:24816
	ds_read_b32 v173, v130 offset:25072
	ds_read_b32 v174, v130 offset:24288
	ds_read_b32 v175, v130 offset:24544
	ds_read_b32 v176, v130 offset:23760
	ds_read_b32 v177, v130 offset:24016
	ds_read_b32 v178, v130 offset:23232
	ds_read_b32 v179, v130 offset:23488
	ds_read_b32 v180, v130 offset:22704
	ds_read_b32 v181, v130 offset:22960
	ds_read_b32 v182, v130 offset:22176
	ds_read_b32 v183, v130 offset:22432
	ds_read_b32 v184, v130 offset:21648
	ds_read_b32 v185, v130 offset:21904
	ds_read_b32 v186, v130 offset:21120
	ds_read_b32 v187, v130 offset:21376
	ds_read_b32 v188, v130 offset:20592
	ds_read_b32 v189, v130 offset:20848
	ds_read_b32 v190, v130 offset:20064
	ds_read_b32 v191, v130 offset:20320
	ds_read_b32 v192, v130 offset:19536
	ds_read_b32 v193, v130 offset:19792
	ds_read_b32 v194, v130 offset:19008
	ds_read_b32 v195, v130 offset:19264
	ds_read_b32 v196, v130 offset:18480
	ds_read_b32 v197, v130 offset:18736
	ds_read_b32 v198, v130 offset:17952
	ds_read_b32 v199, v130 offset:18208
	ds_read_b32 v200, v130 offset:17424
	ds_read_b32 v201, v130 offset:17680
	ds_read_b32 v202, v130 offset:16896
	ds_read_b32 v203, v130 offset:17152
	s_waitcnt lgkmcnt(0)
; __device__ __forceinline__ unsigned f2bf(float f) { unsigned u = __builtin_bit_cast(unsigned, f); return (u + 0x7fffu + ((u >> 16) & 1u)) >> 16; }
; __device__ __forceinline__ void s2_phase(const float* SBUF, bf16_t* ACOMB, const float* lamT, int bx, int tid) {
;     ...
;     for (int blk = 0; blk < 2; ++blk) {
;         float sr[32], si[32];
; #pragma unroll
;         for (int k = 0; k < 32; ++k) { const int c = (d == 0) ? (blk * 32 + k) : (63 - (blk * 32 + k)); sr[k] = sp[(size_t)c * 256]; si[k] = sp[(size_t)c * 256 + 64]; }
; #pragma unroll
;         for (int k = 0; k < 32; ++k) { const int c = (d == 0) ? (blk * 32 + k) : (63 - (blk * 32 + k));
;             xp[(size_t)c * KA] = (bf16_t)f2bf(xr); xp[(size_t)c * KA + 64] = (bf16_t)f2bf(xi);
;             const float nr = lr * xr - li * xi + sr[k], ni = lr * xi + li * xr + si[k]; xr = nr; xi = ni; }
	ds_write_b32 v130, v136 offset:33264
	ds_write_b32 v130, v137 offset:33520
	v_fma_f32 v138, v204, v136, v140
	v_fma_f32 v139, v204, v137, v141
	v_fma_f32 v138, -v205, v137, v138
	v_fma_f32 v139, v205, v136, v139
	ds_write_b32 v130, v138 offset:32736
	ds_write_b32 v130, v139 offset:32992
	v_fma_f32 v136, v204, v138, v142
	v_fma_f32 v137, v204, v139, v143
	v_fma_f32 v136, -v205, v139, v136
	v_fma_f32 v137, v205, v138, v137
	ds_write_b32 v130, v136 offset:32208
	ds_write_b32 v130, v137 offset:32464
	v_fma_f32 v138, v204, v136, v144
	v_fma_f32 v139, v204, v137, v145
	v_fma_f32 v138, -v205, v137, v138
	v_fma_f32 v139, v205, v136, v139
	ds_write_b32 v130, v138 offset:31680
	ds_write_b32 v130, v139 offset:31936
	v_fma_f32 v136, v204, v138, v146
	v_fma_f32 v137, v204, v139, v147
	v_fma_f32 v136, -v205, v139, v136
	v_fma_f32 v137, v205, v138, v137
	ds_write_b32 v130, v136 offset:31152
	ds_write_b32 v130, v137 offset:31408
	v_fma_f32 v138, v204, v136, v148
	v_fma_f32 v139, v204, v137, v149
	v_fma_f32 v138, -v205, v137, v138
	v_fma_f32 v139, v205, v136, v139
	ds_write_b32 v130, v138 offset:30624
	ds_write_b32 v130, v139 offset:30880
	v_fma_f32 v136, v204, v138, v150
	v_fma_f32 v137, v204, v139, v151
	v_fma_f32 v136, -v205, v139, v136
	v_fma_f32 v137, v205, v138, v137
	ds_write_b32 v130, v136 offset:30096
	ds_write_b32 v130, v137 offset:30352
	v_fma_f32 v138, v204, v136, v152
	v_fma_f32 v139, v204, v137, v153
	v_fma_f32 v138, -v205, v137, v138
	v_fma_f32 v139, v205, v136, v139
	ds_write_b32 v130, v138 offset:29568
	ds_write_b32 v130, v139 offset:29824
	v_fma_f32 v136, v204, v138, v154
	v_fma_f32 v137, v204, v139, v155
	v_fma_f32 v136, -v205, v139, v136
	v_fma_f32 v137, v205, v138, v137
	ds_write_b32 v130, v136 offset:29040
	ds_write_b32 v130, v137 offset:29296
	v_fma_f32 v138, v204, v136, v156
	v_fma_f32 v139, v204, v137, v157
	v_fma_f32 v138, -v205, v137, v138
	v_fma_f32 v139, v205, v136, v139
	ds_write_b32 v130, v138 offset:28512
	ds_write_b32 v130, v139 offset:28768
	v_fma_f32 v136, v204, v138, v158
	v_fma_f32 v137, v204, v139, v159
	v_fma_f32 v136, -v205, v139, v136
	v_fma_f32 v137, v205, v138, v137
	ds_write_b32 v130, v136 offset:27984
	ds_write_b32 v130, v137 offset:28240
	v_fma_f32 v138, v204, v136, v160
	v_fma_f32 v139, v204, v137, v161
	v_fma_f32 v138, -v205, v137, v138
	v_fma_f32 v139, v205, v136, v139
	ds_write_b32 v130, v138 offset:27456
	ds_write_b32 v130, v139 offset:27712
	v_fma_f32 v136, v204, v138, v162
	v_fma_f32 v137, v204, v139, v163
	v_fma_f32 v136, -v205, v139, v136
	v_fma_f32 v137, v205, v138, v137
	ds_write_b32 v130, v136 offset:26928
	ds_write_b32 v130, v137 offset:27184
	v_fma_f32 v138, v204, v136, v164
	v_fma_f32 v139, v204, v137, v165
	v_fma_f32 v138, -v205, v137, v138
	v_fma_f32 v139, v205, v136, v139
	ds_write_b32 v130, v138 offset:26400
	ds_write_b32 v130, v139 offset:26656
	v_fma_f32 v136, v204, v138, v166
	v_fma_f32 v137, v204, v139, v167
	v_fma_f32 v136, -v205, v139, v136
	v_fma_f32 v137, v205, v138, v137
	ds_write_b32 v130, v136 offset:25872
	ds_write_b32 v130, v137 offset:26128
	v_fma_f32 v138, v204, v136, v168
	v_fma_f32 v139, v204, v137, v169
	v_fma_f32 v138, -v205, v137, v138
	v_fma_f32 v139, v205, v136, v139
	ds_write_b32 v130, v138 offset:25344
	ds_write_b32 v130, v139 offset:25600
	v_fma_f32 v136, v204, v138, v170
	v_fma_f32 v137, v204, v139, v171
	v_fma_f32 v136, -v205, v139, v136
	v_fma_f32 v137, v205, v138, v137
	ds_write_b32 v130, v136 offset:24816
	ds_write_b32 v130, v137 offset:25072
	v_fma_f32 v138, v204, v136, v172
	v_fma_f32 v139, v204, v137, v173
	v_fma_f32 v138, -v205, v137, v138
	v_fma_f32 v139, v205, v136, v139
	ds_write_b32 v130, v138 offset:24288
	ds_write_b32 v130, v139 offset:24544
	v_fma_f32 v136, v204, v138, v174
	v_fma_f32 v137, v204, v139, v175
	v_fma_f32 v136, -v205, v139, v136
	v_fma_f32 v137, v205, v138, v137
	ds_write_b32 v130, v136 offset:23760
	ds_write_b32 v130, v137 offset:24016
	v_fma_f32 v138, v204, v136, v176
	v_fma_f32 v139, v204, v137, v177
	v_fma_f32 v138, -v205, v137, v138
	v_fma_f32 v139, v205, v136, v139
	ds_write_b32 v130, v138 offset:23232
	ds_write_b32 v130, v139 offset:23488
	v_fma_f32 v136, v204, v138, v178
	v_fma_f32 v137, v204, v139, v179
	v_fma_f32 v136, -v205, v139, v136
	v_fma_f32 v137, v205, v138, v137
	ds_write_b32 v130, v136 offset:22704
	ds_write_b32 v130, v137 offset:22960
	v_fma_f32 v138, v204, v136, v180
	v_fma_f32 v139, v204, v137, v181
	v_fma_f32 v138, -v205, v137, v138
	v_fma_f32 v139, v205, v136, v139
	ds_write_b32 v130, v138 offset:22176
	ds_write_b32 v130, v139 offset:22432
	v_fma_f32 v136, v204, v138, v182
	v_fma_f32 v137, v204, v139, v183
	v_fma_f32 v136, -v205, v139, v136
	v_fma_f32 v137, v205, v138, v137
	ds_write_b32 v130, v136 offset:21648
	ds_write_b32 v130, v137 offset:21904
	v_fma_f32 v138, v204, v136, v184
	v_fma_f32 v139, v204, v137, v185
	v_fma_f32 v138, -v205, v137, v138
	v_fma_f32 v139, v205, v136, v139
	ds_write_b32 v130, v138 offset:21120
	ds_write_b32 v130, v139 offset:21376
	v_fma_f32 v136, v204, v138, v186
	v_fma_f32 v137, v204, v139, v187
	v_fma_f32 v136, -v205, v139, v136
	v_fma_f32 v137, v205, v138, v137
	ds_write_b32 v130, v136 offset:20592
	ds_write_b32 v130, v137 offset:20848
	v_fma_f32 v138, v204, v136, v188
	v_fma_f32 v139, v204, v137, v189
	v_fma_f32 v138, -v205, v137, v138
	v_fma_f32 v139, v205, v136, v139
	ds_write_b32 v130, v138 offset:20064
	ds_write_b32 v130, v139 offset:20320
	v_fma_f32 v136, v204, v138, v190
	v_fma_f32 v137, v204, v139, v191
	v_fma_f32 v136, -v205, v139, v136
	v_fma_f32 v137, v205, v138, v137
	ds_write_b32 v130, v136 offset:19536
	ds_write_b32 v130, v137 offset:19792
	v_fma_f32 v138, v204, v136, v192
; __device__ __forceinline__ unsigned f2bf(float f) { unsigned u = __builtin_bit_cast(unsigned, f); return (u + 0x7fffu + ((u >> 16) & 1u)) >> 16; }
; __device__ __forceinline__ void s2_phase(const float* SBUF, bf16_t* ACOMB, const float* lamT, int bx, int tid) {
;     ...
;     for (int blk = 0; blk < 2; ++blk) {
;         float sr[32], si[32];
; #pragma unroll
;         for (int k = 0; k < 32; ++k) { const int c = (d == 0) ? (blk * 32 + k) : (63 - (blk * 32 + k)); sr[k] = sp[(size_t)c * 256]; si[k] = sp[(size_t)c * 256 + 64]; }
; #pragma unroll
;         for (int k = 0; k < 32; ++k) { const int c = (d == 0) ? (blk * 32 + k) : (63 - (blk * 32 + k));
;             xp[(size_t)c * KA] = (bf16_t)f2bf(xr); xp[(size_t)c * KA + 64] = (bf16_t)f2bf(xi);
;             const float nr = lr * xr - li * xi + sr[k], ni = lr * xi + li * xr + si[k]; xr = nr; xi = ni; }
	v_fma_f32 v139, v204, v137, v193
	v_fma_f32 v138, -v205, v137, v138
	v_fma_f32 v139, v205, v136, v139
	ds_write_b32 v130, v138 offset:19008
	ds_write_b32 v130, v139 offset:19264
	v_fma_f32 v136, v204, v138, v194
	v_fma_f32 v137, v204, v139, v195
	v_fma_f32 v136, -v205, v139, v136
	v_fma_f32 v137, v205, v138, v137
	ds_write_b32 v130, v136 offset:18480
	ds_write_b32 v130, v137 offset:18736
	v_fma_f32 v138, v204, v136, v196
	v_fma_f32 v139, v204, v137, v197
	v_fma_f32 v138, -v205, v137, v138
	v_fma_f32 v139, v205, v136, v139
	ds_write_b32 v130, v138 offset:17952
	ds_write_b32 v130, v139 offset:18208
	v_fma_f32 v136, v204, v138, v198
	v_fma_f32 v137, v204, v139, v199
	v_fma_f32 v136, -v205, v139, v136
	v_fma_f32 v137, v205, v138, v137
	ds_write_b32 v130, v136 offset:17424
	ds_write_b32 v130, v137 offset:17680
	v_fma_f32 v138, v204, v136, v200
	v_fma_f32 v139, v204, v137, v201
	v_fma_f32 v138, -v205, v137, v138
	v_fma_f32 v139, v205, v136, v139
	ds_write_b32 v130, v138 offset:16896
	ds_write_b32 v130, v139 offset:17152
	v_fma_f32 v136, v204, v138, v202
	v_fma_f32 v137, v204, v139, v203
	v_fma_f32 v136, -v205, v139, v136
	v_fma_f32 v137, v205, v138, v137
	ds_read_b32 v140, v130 offset:16368
	ds_read_b32 v141, v130 offset:16624
	ds_read_b32 v142, v130 offset:15840
	ds_read_b32 v143, v130 offset:16096
	ds_read_b32 v144, v130 offset:15312
	ds_read_b32 v145, v130 offset:15568
	ds_read_b32 v146, v130 offset:14784
	ds_read_b32 v147, v130 offset:15040
	ds_read_b32 v148, v130 offset:14256
	ds_read_b32 v149, v130 offset:14512
	ds_read_b32 v150, v130 offset:13728
	ds_read_b32 v151, v130 offset:13984
	ds_read_b32 v152, v130 offset:13200
	ds_read_b32 v153, v130 offset:13456
	ds_read_b32 v154, v130 offset:12672
	ds_read_b32 v155, v130 offset:12928
	ds_read_b32 v156, v130 offset:12144
	ds_read_b32 v157, v130 offset:12400
	ds_read_b32 v158, v130 offset:11616
	ds_read_b32 v159, v130 offset:11872
	ds_read_b32 v160, v130 offset:11088
	ds_read_b32 v161, v130 offset:11344
	ds_read_b32 v162, v130 offset:10560
	ds_read_b32 v163, v130 offset:10816
	ds_read_b32 v164, v130 offset:10032
	ds_read_b32 v165, v130 offset:10288
	ds_read_b32 v166, v130 offset:9504
	ds_read_b32 v167, v130 offset:9760
	ds_read_b32 v168, v130 offset:8976
	ds_read_b32 v169, v130 offset:9232
	ds_read_b32 v170, v130 offset:8448
	ds_read_b32 v171, v130 offset:8704
	ds_read_b32 v172, v130 offset:7920
	ds_read_b32 v173, v130 offset:8176
	ds_read_b32 v174, v130 offset:7392
	ds_read_b32 v175, v130 offset:7648
	ds_read_b32 v176, v130 offset:6864
	ds_read_b32 v177, v130 offset:7120
	ds_read_b32 v178, v130 offset:6336
	ds_read_b32 v179, v130 offset:6592
	ds_read_b32 v180, v130 offset:5808
	ds_read_b32 v181, v130 offset:6064
	ds_read_b32 v182, v130 offset:5280
	ds_read_b32 v183, v130 offset:5536
	ds_read_b32 v184, v130 offset:4752
	ds_read_b32 v185, v130 offset:5008
	ds_read_b32 v186, v130 offset:4224
	ds_read_b32 v187, v130 offset:4480
	ds_read_b32 v188, v130 offset:3696
	ds_read_b32 v189, v130 offset:3952
	ds_read_b32 v190, v130 offset:3168
	ds_read_b32 v191, v130 offset:3424
	ds_read_b32 v192, v130 offset:2640
	ds_read_b32 v193, v130 offset:2896
	ds_read_b32 v194, v130 offset:2112
	ds_read_b32 v195, v130 offset:2368
	ds_read_b32 v196, v130 offset:1584
	ds_read_b32 v197, v130 offset:1840
	ds_read_b32 v198, v130 offset:1056
	ds_read_b32 v199, v130 offset:1312
	ds_read_b32 v200, v130 offset:528
	ds_read_b32 v201, v130 offset:784
	ds_read_b32 v202, v130 offset:0
	ds_read_b32 v203, v130 offset:256
	s_waitcnt lgkmcnt(0)
	ds_write_b32 v130, v136 offset:16368
	ds_write_b32 v130, v137 offset:16624
	v_fma_f32 v138, v204, v136, v140
	v_fma_f32 v139, v204, v137, v141
	v_fma_f32 v138, -v205, v137, v138
	v_fma_f32 v139, v205, v136, v139
	ds_write_b32 v130, v138 offset:15840
	ds_write_b32 v130, v139 offset:16096
	v_fma_f32 v136, v204, v138, v142
	v_fma_f32 v137, v204, v139, v143
	v_fma_f32 v136, -v205, v139, v136
	v_fma_f32 v137, v205, v138, v137
	ds_write_b32 v130, v136 offset:15312
	ds_write_b32 v130, v137 offset:15568
	v_fma_f32 v138, v204, v136, v144
	v_fma_f32 v139, v204, v137, v145
	v_fma_f32 v138, -v205, v137, v138
	v_fma_f32 v139, v205, v136, v139
	ds_write_b32 v130, v138 offset:14784
	ds_write_b32 v130, v139 offset:15040
	v_fma_f32 v136, v204, v138, v146
	v_fma_f32 v137, v204, v139, v147
	v_fma_f32 v136, -v205, v139, v136
	v_fma_f32 v137, v205, v138, v137
	ds_write_b32 v130, v136 offset:14256
	ds_write_b32 v130, v137 offset:14512
	v_fma_f32 v138, v204, v136, v148
	v_fma_f32 v139, v204, v137, v149
	v_fma_f32 v138, -v205, v137, v138
	v_fma_f32 v139, v205, v136, v139
	ds_write_b32 v130, v138 offset:13728
	ds_write_b32 v130, v139 offset:13984
	v_fma_f32 v136, v204, v138, v150
	v_fma_f32 v137, v204, v139, v151
	v_fma_f32 v136, -v205, v139, v136
	v_fma_f32 v137, v205, v138, v137
	ds_write_b32 v130, v136 offset:13200
	ds_write_b32 v130, v137 offset:13456
	v_fma_f32 v138, v204, v136, v152
	v_fma_f32 v139, v204, v137, v153
	v_fma_f32 v138, -v205, v137, v138
	v_fma_f32 v139, v205, v136, v139
	ds_write_b32 v130, v138 offset:12672
	ds_write_b32 v130, v139 offset:12928
	v_fma_f32 v136, v204, v138, v154
	v_fma_f32 v137, v204, v139, v155
	v_fma_f32 v136, -v205, v139, v136
	v_fma_f32 v137, v205, v138, v137
	ds_write_b32 v130, v136 offset:12144
	ds_write_b32 v130, v137 offset:12400
	v_fma_f32 v138, v204, v136, v156
	v_fma_f32 v139, v204, v137, v157
	v_fma_f32 v138, -v205, v137, v138
	v_fma_f32 v139, v205, v136, v139
	ds_write_b32 v130, v138 offset:11616
	ds_write_b32 v130, v139 offset:11872
	v_fma_f32 v136, v204, v138, v158
	v_fma_f32 v137, v204, v139, v159
	v_fma_f32 v136, -v205, v139, v136
	v_fma_f32 v137, v205, v138, v137
; __device__ __forceinline__ unsigned f2bf(float f) { unsigned u = __builtin_bit_cast(unsigned, f); return (u + 0x7fffu + ((u >> 16) & 1u)) >> 16; }
; __device__ __forceinline__ void s2_phase(const float* SBUF, bf16_t* ACOMB, const float* lamT, int bx, int tid) {
;     ...
;     for (int blk = 0; blk < 2; ++blk) {
;         float sr[32], si[32];
; #pragma unroll
;         for (int k = 0; k < 32; ++k) { const int c = (d == 0) ? (blk * 32 + k) : (63 - (blk * 32 + k)); sr[k] = sp[(size_t)c * 256]; si[k] = sp[(size_t)c * 256 + 64]; }
; #pragma unroll
;         for (int k = 0; k < 32; ++k) { const int c = (d == 0) ? (blk * 32 + k) : (63 - (blk * 32 + k));
;             xp[(size_t)c * KA] = (bf16_t)f2bf(xr); xp[(size_t)c * KA + 64] = (bf16_t)f2bf(xi);
;             const float nr = lr * xr - li * xi + sr[k], ni = lr * xi + li * xr + si[k]; xr = nr; xi = ni; }
	ds_write_b32 v130, v136 offset:11088
	ds_write_b32 v130, v137 offset:11344
	v_fma_f32 v138, v204, v136, v160
	v_fma_f32 v139, v204, v137, v161
	v_fma_f32 v138, -v205, v137, v138
	v_fma_f32 v139, v205, v136, v139
	ds_write_b32 v130, v138 offset:10560
	ds_write_b32 v130, v139 offset:10816
	v_fma_f32 v136, v204, v138, v162
	v_fma_f32 v137, v204, v139, v163
	v_fma_f32 v136, -v205, v139, v136
	v_fma_f32 v137, v205, v138, v137
	ds_write_b32 v130, v136 offset:10032
	ds_write_b32 v130, v137 offset:10288
	v_fma_f32 v138, v204, v136, v164
	v_fma_f32 v139, v204, v137, v165
	v_fma_f32 v138, -v205, v137, v138
	v_fma_f32 v139, v205, v136, v139
	ds_write_b32 v130, v138 offset:9504
	ds_write_b32 v130, v139 offset:9760
	v_fma_f32 v136, v204, v138, v166
	v_fma_f32 v137, v204, v139, v167
	v_fma_f32 v136, -v205, v139, v136
	v_fma_f32 v137, v205, v138, v137
	ds_write_b32 v130, v136 offset:8976
	ds_write_b32 v130, v137 offset:9232
	v_fma_f32 v138, v204, v136, v168
	v_fma_f32 v139, v204, v137, v169
	v_fma_f32 v138, -v205, v137, v138
	v_fma_f32 v139, v205, v136, v139
	ds_write_b32 v130, v138 offset:8448
	ds_write_b32 v130, v139 offset:8704
	v_fma_f32 v136, v204, v138, v170
	v_fma_f32 v137, v204, v139, v171
	v_fma_f32 v136, -v205, v139, v136
	v_fma_f32 v137, v205, v138, v137
	ds_write_b32 v130, v136 offset:7920
	ds_write_b32 v130, v137 offset:8176
	v_fma_f32 v138, v204, v136, v172
	v_fma_f32 v139, v204, v137, v173
	v_fma_f32 v138, -v205, v137, v138
	v_fma_f32 v139, v205, v136, v139
	ds_write_b32 v130, v138 offset:7392
	ds_write_b32 v130, v139 offset:7648
	v_fma_f32 v136, v204, v138, v174
	v_fma_f32 v137, v204, v139, v175
	v_fma_f32 v136, -v205, v139, v136
	v_fma_f32 v137, v205, v138, v137
	ds_write_b32 v130, v136 offset:6864
	ds_write_b32 v130, v137 offset:7120
	v_fma_f32 v138, v204, v136, v176
	v_fma_f32 v139, v204, v137, v177
	v_fma_f32 v138, -v205, v137, v138
	v_fma_f32 v139, v205, v136, v139
	ds_write_b32 v130, v138 offset:6336
	ds_write_b32 v130, v139 offset:6592
	v_fma_f32 v136, v204, v138, v178
	v_fma_f32 v137, v204, v139, v179
	v_fma_f32 v136, -v205, v139, v136
	v_fma_f32 v137, v205, v138, v137
	ds_write_b32 v130, v136 offset:5808
	ds_write_b32 v130, v137 offset:6064
	v_fma_f32 v138, v204, v136, v180
	v_fma_f32 v139, v204, v137, v181
	v_fma_f32 v138, -v205, v137, v138
	v_fma_f32 v139, v205, v136, v139
	ds_write_b32 v130, v138 offset:5280
	ds_write_b32 v130, v139 offset:5536
	v_fma_f32 v136, v204, v138, v182
	v_fma_f32 v137, v204, v139, v183
	v_fma_f32 v136, -v205, v139, v136
	v_fma_f32 v137, v205, v138, v137
	ds_write_b32 v130, v136 offset:4752
	ds_write_b32 v130, v137 offset:5008
	v_fma_f32 v138, v204, v136, v184
	v_fma_f32 v139, v204, v137, v185
	v_fma_f32 v138, -v205, v137, v138
	v_fma_f32 v139, v205, v136, v139
	ds_write_b32 v130, v138 offset:4224
	ds_write_b32 v130, v139 offset:4480
	v_fma_f32 v136, v204, v138, v186
	v_fma_f32 v137, v204, v139, v187
	v_fma_f32 v136, -v205, v139, v136
	v_fma_f32 v137, v205, v138, v137
	ds_write_b32 v130, v136 offset:3696
	ds_write_b32 v130, v137 offset:3952
	v_fma_f32 v138, v204, v136, v188
	v_fma_f32 v139, v204, v137, v189
	v_fma_f32 v138, -v205, v137, v138
	v_fma_f32 v139, v205, v136, v139
	ds_write_b32 v130, v138 offset:3168
	ds_write_b32 v130, v139 offset:3424
	v_fma_f32 v136, v204, v138, v190
	v_fma_f32 v137, v204, v139, v191
	v_fma_f32 v136, -v205, v139, v136
	v_fma_f32 v137, v205, v138, v137
	ds_write_b32 v130, v136 offset:2640
	ds_write_b32 v130, v137 offset:2896
	v_fma_f32 v138, v204, v136, v192
	v_fma_f32 v139, v204, v137, v193
	v_fma_f32 v138, -v205, v137, v138
	v_fma_f32 v139, v205, v136, v139
	ds_write_b32 v130, v138 offset:2112
	ds_write_b32 v130, v139 offset:2368
	v_fma_f32 v136, v204, v138, v194
	v_fma_f32 v137, v204, v139, v195
	v_fma_f32 v136, -v205, v139, v136
	v_fma_f32 v137, v205, v138, v137
	ds_write_b32 v130, v136 offset:1584
	ds_write_b32 v130, v137 offset:1840
	v_fma_f32 v138, v204, v136, v196
	v_fma_f32 v139, v204, v137, v197
	v_fma_f32 v138, -v205, v137, v138
	v_fma_f32 v139, v205, v136, v139
	ds_write_b32 v130, v138 offset:1056
	ds_write_b32 v130, v139 offset:1312
	v_fma_f32 v136, v204, v138, v198
	v_fma_f32 v137, v204, v139, v199
	v_fma_f32 v136, -v205, v139, v136
	v_fma_f32 v137, v205, v138, v137
	ds_write_b32 v130, v136 offset:528
	ds_write_b32 v130, v137 offset:784
	v_fma_f32 v138, v204, v136, v200
	v_fma_f32 v139, v204, v137, v201
	v_fma_f32 v138, -v205, v137, v138
	v_fma_f32 v139, v205, v136, v139
	ds_write_b32 v130, v138 offset:0
	ds_write_b32 v130, v139 offset:256
	v_fma_f32 v136, v204, v138, v202
	v_fma_f32 v137, v204, v139, v203
	v_fma_f32 v136, -v205, v139, v136
	v_fma_f32 v137, v205, v138, v137
; __device__ __forceinline__ unsigned f2bf(float f) { unsigned u = __builtin_bit_cast(unsigned, f); return (u + 0x7fffu + ((u >> 16) & 1u)) >> 16; }
; __device__ __forceinline__ void s2_phase(const float* SBUF, bf16_t* ACOMB, const float* lamT, int bx, int tid) {
;     ...
;         for (int k = 0; k < 32; ++k) { const int c = (d == 0) ? (blk * 32 + k) : (63 - (blk * 32 + k));
;             xp[(size_t)c * KA] = (bf16_t)f2bf(xr); xp[(size_t)c * KA + 64] = (bf16_t)f2bf(xi);
;             const float nr = lr * xr - li * xi + sr[k], ni = lr * xi + li * xr + si[k]; xr = nr; xi = ni; }
.Ls1f_scan_done_1:
	s_waitcnt lgkmcnt(0)
	s_barrier
	ds_read_b128 v[140:143], v131 offset:0
	ds_read_b128 v[144:147], v131 offset:16
	ds_read_b128 v[148:151], v131 offset:16896
	ds_read_b128 v[152:155], v131 offset:16912
	ds_read_b128 v[156:159], v131 offset:33792
	ds_read_b128 v[160:163], v131 offset:33808
	ds_read_b128 v[164:167], v131 offset:50688
	ds_read_b128 v[168:171], v131 offset:50704
	ds_read_b128 v[172:175], v132 offset:0
	ds_read_b128 v[176:179], v132 offset:16
	ds_read_b128 v[180:183], v132 offset:16896
	ds_read_b128 v[184:187], v132 offset:16912
	ds_read_b128 v[188:191], v132 offset:33792
	ds_read_b128 v[192:195], v132 offset:33808
	ds_read_b128 v[196:199], v132 offset:50688
	ds_read_b128 v[200:203], v132 offset:50704
	s_waitcnt lgkmcnt(14)
	v_cvt_pk_bf16_f32 v140, v140, v141
	v_cvt_pk_bf16_f32 v141, v142, v143
	v_cvt_pk_bf16_f32 v142, v144, v145
	v_cvt_pk_bf16_f32 v143, v146, v147
	v_mov_b32_e32 v206, v133
	global_store_dwordx4 v206, v[140:143], s[6:7] offset:256
	s_waitcnt lgkmcnt(12)
	v_cvt_pk_bf16_f32 v148, v148, v149
	v_cvt_pk_bf16_f32 v149, v150, v151
	v_cvt_pk_bf16_f32 v150, v152, v153
	v_cvt_pk_bf16_f32 v151, v154, v155
	v_add_u32_e32 v207, 0xc000, v133
	global_store_dwordx4 v207, v[148:151], s[6:7] offset:256
	s_waitcnt lgkmcnt(10)
	v_cvt_pk_bf16_f32 v156, v156, v157
	v_cvt_pk_bf16_f32 v157, v158, v159
	v_cvt_pk_bf16_f32 v158, v160, v161
	v_cvt_pk_bf16_f32 v159, v162, v163
	v_add_u32_e32 v208, 0x18000, v133
	global_store_dwordx4 v208, v[156:159], s[6:7] offset:256
	s_waitcnt lgkmcnt(8)
	v_cvt_pk_bf16_f32 v164, v164, v165
	v_cvt_pk_bf16_f32 v165, v166, v167
	v_cvt_pk_bf16_f32 v166, v168, v169
	v_cvt_pk_bf16_f32 v167, v170, v171
	v_add_u32_e32 v209, 0x24000, v133
	global_store_dwordx4 v209, v[164:167], s[6:7] offset:256
	s_waitcnt lgkmcnt(6)
	v_cvt_pk_bf16_f32 v172, v172, v173
	v_cvt_pk_bf16_f32 v173, v174, v175
	v_cvt_pk_bf16_f32 v174, v176, v177
	v_cvt_pk_bf16_f32 v175, v178, v179
	v_add_u32_e32 v210, 0x30000, v133
	global_store_dwordx4 v210, v[172:175], s[6:7] offset:256
	s_waitcnt lgkmcnt(4)
	v_cvt_pk_bf16_f32 v180, v180, v181
	v_cvt_pk_bf16_f32 v181, v182, v183
	v_cvt_pk_bf16_f32 v182, v184, v185
	v_cvt_pk_bf16_f32 v183, v186, v187
	v_add_u32_e32 v211, 0x3c000, v133
	global_store_dwordx4 v211, v[180:183], s[6:7] offset:256
	s_waitcnt lgkmcnt(2)
	v_cvt_pk_bf16_f32 v188, v188, v189
	v_cvt_pk_bf16_f32 v189, v190, v191
	v_cvt_pk_bf16_f32 v190, v192, v193
	v_cvt_pk_bf16_f32 v191, v194, v195
	v_add_u32_e32 v212, 0x48000, v133
	global_store_dwordx4 v212, v[188:191], s[6:7] offset:256
	s_waitcnt lgkmcnt(0)
	v_cvt_pk_bf16_f32 v196, v196, v197
	v_cvt_pk_bf16_f32 v197, v198, v199
	v_cvt_pk_bf16_f32 v198, v200, v201
	v_cvt_pk_bf16_f32 v199, v202, v203
	v_add_u32_e32 v213, 0x54000, v133
	global_store_dwordx4 v213, v[196:199], s[6:7] offset:256
	s_barrier
	s_branch .LBB0_453

; #define PH_TID() const int tid = opaque_tid(), lane = tid & 63, wave = __builtin_amdgcn_readfirstlane(tid >> 6), gw = bx * 8 + wave; (void)lane; (void)gw; KArgsPtr ap = kargs()
; #define GSYNC() do { XSYNC1(); if (PROBE_SYNC) XSYNC1(); } while (0)
; __global__ void __launch_bounds__(512, 2) fwd_megakernel(Args a_unused) {
;     ...
;         GSYNC();
;         for (int rep = 0; rep <= ((PROBE_SSM >> 1) & 1); ++rep) { PH_TID(); s2_phase(WSP(float, WS_SBUF), WSP(bf16_t, WS_ACOMB), WSP(float, WS_LAMT) + layer * LAMT_L, bx, tid); }
.LBB0_398:
	s_branch .LBB0_453
